# first grid barrier: the 16 per-XCC census counter loads issued together (one round trip instead of 14 serialized)
# speedup vs baseline: 1.0046x; 1.0046x over previous
.LBB0_165:
	s_waitcnt lgkmcnt(0)
	global_load_dword v15, v33, s[56:57] sc1
	global_load_dword v14, v33, s[58:59] sc1
	global_load_dword v13, v33, s[60:61] sc1
	v_readlane_b32 s0, v251, 45
	v_readlane_b32 s1, v251, 46
	s_nop 4
	global_load_dword v12, v33, s[0:1] sc1
	v_readlane_b32 s0, v251, 47
	v_readlane_b32 s1, v251, 48
	s_nop 4
	global_load_dword v11, v33, s[0:1] sc1
	v_readlane_b32 s0, v251, 49
	v_readlane_b32 s1, v251, 50
	s_nop 4
	global_load_dword v10, v33, s[0:1] sc1
	v_readlane_b32 s0, v251, 51
	v_readlane_b32 s1, v251, 52
	s_nop 4
	global_load_dword v9, v33, s[0:1] sc1
	v_readlane_b32 s0, v251, 53
	v_readlane_b32 s1, v251, 54
	s_nop 4
	global_load_dword v8, v33, s[0:1] sc1
	v_readlane_b32 s0, v251, 55
	v_readlane_b32 s1, v251, 56
	s_nop 4
	global_load_dword v7, v33, s[0:1] sc1
	v_readlane_b32 s0, v251, 57
	v_readlane_b32 s1, v251, 58
	s_nop 4
	global_load_dword v6, v33, s[0:1] sc1
	v_readlane_b32 s0, v251, 59
	v_readlane_b32 s1, v251, 60
	s_nop 4
	global_load_dword v5, v33, s[0:1] sc1
	v_readlane_b32 s0, v251, 61
	v_readlane_b32 s1, v251, 62
	s_nop 4
	global_load_dword v4, v33, s[0:1] sc1
	v_readlane_b32 s0, v251, 63
	v_readlane_b32 s1, v252, 0
	s_nop 4
	global_load_dword v3, v33, s[0:1] sc1
	v_readlane_b32 s0, v252, 1
	v_readlane_b32 s1, v252, 2
	s_nop 4
	global_load_dword v2, v33, s[0:1] sc1
	v_readlane_b32 s0, v252, 3
	v_readlane_b32 s1, v252, 4
	s_nop 4
	global_load_dword v1, v33, s[0:1] sc1
	v_readlane_b32 s0, v252, 5
	v_readlane_b32 s1, v252, 6
	s_nop 4
	global_load_dword v0, v33, s[0:1] sc1
	s_load_dword s2, s[64:65], 0x0
	s_waitcnt vmcnt(0)
	v_readfirstlane_b32 s86, v15
	v_add_u32_e32 v15, v14, v15
	v_add_u32_e32 v15, v15, v13
	v_add_u32_e32 v15, v15, v12
	v_add_u32_e32 v15, v15, v11
	v_add_u32_e32 v15, v15, v10
	v_add_u32_e32 v15, v15, v9
	v_add_u32_e32 v15, v15, v8
	v_add_u32_e32 v15, v15, v7
	v_add_u32_e32 v15, v15, v6
	v_add_u32_e32 v15, v15, v5
	v_add_u32_e32 v15, v15, v4
	v_add_u32_e32 v15, v15, v3
	v_add_u32_e32 v15, v15, v2
	v_add_u32_e32 v15, v15, v1
	v_add_u32_e32 v15, v15, v0
	s_mov_b64 s[0:1], -1
	s_waitcnt lgkmcnt(0)
	v_cmp_eq_u32_e32 vcc, s2, v15
	s_mov_b64 s[2:3], -1
	s_cbranch_vccnz .LBB0_164
	s_and_b32 s0, s6, 0xff
	s_cmp_eq_u32 s0, 0
	s_mov_b64 s[0:1], -1
	s_mov_b64 s[4:5], -1
	s_sleep 1
	s_cbranch_scc1 .LBB0_169
	s_and_b64 vcc, exec, s[4:5]
	s_cbranch_vccz .LBB0_164
